# cache-policy hint: nt on the in-projection P tile stores (16 per unit)
# speedup vs baseline: 1.0007x; 1.0007x over previous
; #define PG8_STAGE(bufoff, gbase, voff) do { _Pragma("unroll") for (int _i = 0; _i < 2; ++_i) \
;         __builtin_amdgcn_global_load_lds((const unsigned*)((const char*)(gbase) + (voff)[_i]), (PG8_LAS unsigned*)(lds + (bufoff) + ldsw + _i * 8192), 16, 0, 0); } while (0)
; #define PG8_LDA(dst, b, h) do { _Pragma("unroll") for (int m = 0; m < 4; ++m) _Pragma("unroll") for (int k = 0; k < 2; ++k) dst[m][k] = *(const PG8_LAS bf16x8*)(lds + PG8_SA(b, h) + aoff + m * 2048 + k * 1024); } while (0)
; #define PG8_LDB(dst, b, h) do { _Pragma("unroll") for (int n = 0; n < 2; ++n) _Pragma("unroll") for (int k = 0; k < 2; ++k) dst[n][k] = *(const PG8_LAS bf16x8*)(lds + PG8_SB(b, h) + boff + n * 2048 + k * 1024); } while (0)
; #define PG8_MMA(ai, bj, At, Bt) do { __builtin_amdgcn_s_setprio(1); _Pragma("unroll") for (int m = 0; m < 4; ++m) _Pragma("unroll") for (int n = 0; n < 2; ++n) _Pragma("unroll") for (int k = 0; k < 2; ++k) \
;         acc[ai][bj][m][n] = __builtin_amdgcn_mfma_f32_16x16x32_bf16(Bt[n][k], At[m][k], acc[ai][bj][m][n], 0, 0, 0); __builtin_amdgcn_s_setprio(0); } while (0)
; #define PG8_WAIT_V(n) asm volatile("s_waitcnt vmcnt(" #n ")" ::: "memory")
; #define PG8_WAIT_L(n) asm volatile("s_waitcnt lgkmcnt(" #n ")" ::: "memory")
; template <class Epi, class Sched, bool ALIGN_EPI = true>
; __device__ __forceinline__ void gemm_phase(PG8_LAS unsigned char* lds, const Gemm g, const Sched& S, const Epi& E, const int tid) {
;     ...
;         for (int t = 0; t < nt; t += 2) {
;             const bool last = (t == nt - 2);
;             const char* a1 = cA + (size_t)(t + 1) * kstep;
;             const char* a2 = last ? nA : cA + (size_t)(t + 2) * kstep; const char* b2 = last ? nB : cB + (size_t)(t + 2) * kstep;
;             const char* a3 = a2 + kstep; const char* b3 = b2 + kstep;
;             if (last && has_next) S.a_ready(nxt);
;             PG8_LDB(B0, 0, 0); PG8_LDB(B1, 0, 1); PG8_SCHED; PG8_LDA(At, 0, 0); PG8_STAGE(PG8_SA(1, 1), a1 + hstepA, voffA);
;             PG8_WAIT_V(8); PG8_WAIT_L(0); PG8_BAR; PG8_MMA(0, 0, At, B0); PG8_MMA(0, 1, At, B1); PG8_BAR; PG8_SCHED;
;             PG8_LDA(At, 0, 1); PG8_STAGE(PG8_SB(0, 0), b2, voffB); PG8_STAGE(PG8_SB(0, 1), b2 + hstepB, voffB); PG8_STAGE(PG8_SA(0, 0), a2, voffA);
;             PG8_WAIT_V(8); PG8_WAIT_L(0); PG8_BAR; PG8_MMA(1, 0, At, B0); PG8_MMA(1, 1, At, B1); PG8_BAR; PG8_SCHED;
.LBB0_514:
	s_add_u32 s44, s42, 0xfff80080
	s_addc_u32 s45, s43, -1
	s_add_i32 s57, 0, 0x10000
	s_cmp_eq_u32 s56, 28
	s_cselect_b32 s47, s13, s45
	s_cselect_b32 s46, s52, s44
	s_cselect_b32 s45, s23, s55
	s_cselect_b32 s44, s53, s54
	s_add_i32 s60, 0, 0x14000
	v_add_u32_e32 v158, s57, v147
	v_add_u32_e32 v174, s60, v147
	ds_read_b128 v[142:145], v158
	ds_read_b128 v[150:153], v158 offset:1024
	ds_read_b128 v[154:157], v158 offset:2048
	ds_read_b128 v[158:161], v158 offset:3072
	ds_read_b128 v[162:165], v174
	ds_read_b128 v[166:169], v174 offset:1024
	ds_read_b128 v[170:173], v174 offset:2048
	ds_read_b128 v[174:177], v174 offset:3072
	s_add_i32 m0, s7, 0xc000
	ds_read_b128 v[178:181], v149
	ds_read_b128 v[182:185], v149 offset:1024
	ds_read_b128 v[186:189], v149 offset:2048
	ds_read_b128 v[190:193], v149 offset:3072
	ds_read_b128 v[194:197], v149 offset:4096
	ds_read_b128 v[198:201], v149 offset:5120
	ds_read_b128 v[202:205], v149 offset:6144
	ds_read_b128 v[210:213], v149 offset:7168
	global_load_lds_dwordx4 v138, s[42:43]
	s_add_i32 m0, s7, 0xe000
	s_nop 0
	global_load_lds_dwordx4 v140, s[42:43]
	s_waitcnt vmcnt(8)
	s_waitcnt lgkmcnt(0)
	s_barrier
	s_waitcnt lgkmcnt(0)
	v_mfma_f32_16x16x32_bf16 v[128:131], v[142:145], v[178:181], v[128:131]
	v_mfma_f32_16x16x32_bf16 v[128:131], v[150:153], v[182:185], v[128:131]
	v_mfma_f32_16x16x32_bf16 v[124:127], v[158:161], v[182:185], v[124:127]
	v_mfma_f32_16x16x32_bf16 v[124:127], v[154:157], v[178:181], v[124:127]
	v_mfma_f32_16x16x32_bf16 v[112:115], v[154:157], v[186:189], v[112:115]
	v_mfma_f32_16x16x32_bf16 v[112:115], v[158:161], v[190:193], v[112:115]
	v_mfma_f32_16x16x32_bf16 v[120:123], v[150:153], v[190:193], v[120:123]
	v_mfma_f32_16x16x32_bf16 v[120:123], v[142:145], v[186:189], v[120:123]
	v_mfma_f32_16x16x32_bf16 v[104:107], v[142:145], v[194:197], v[104:107]
	v_mfma_f32_16x16x32_bf16 v[104:107], v[150:153], v[198:201], v[104:107]
	v_mfma_f32_16x16x32_bf16 v[96:99], v[158:161], v[198:201], v[96:99]
	v_mfma_f32_16x16x32_bf16 v[96:99], v[154:157], v[194:197], v[96:99]
	v_mfma_f32_16x16x32_bf16 v[80:83], v[154:157], v[202:205], v[80:83]
	v_mfma_f32_16x16x32_bf16 v[80:83], v[158:161], v[210:213], v[80:83]
	v_mfma_f32_16x16x32_bf16 v[88:91], v[150:153], v[210:213], v[88:91]
	v_mfma_f32_16x16x32_bf16 v[88:91], v[142:145], v[202:205], v[88:91]
	v_mfma_f32_16x16x32_bf16 v[116:119], v[162:165], v[178:181], v[116:119]
	v_mfma_f32_16x16x32_bf16 v[116:119], v[166:169], v[182:185], v[116:119]
	v_mfma_f32_16x16x32_bf16 v[108:111], v[174:177], v[182:185], v[108:111]
	v_mfma_f32_16x16x32_bf16 v[108:111], v[170:173], v[178:181], v[108:111]
	v_mfma_f32_16x16x32_bf16 v[92:95], v[170:173], v[186:189], v[92:95]
	v_mfma_f32_16x16x32_bf16 v[92:95], v[174:177], v[190:193], v[92:95]
	v_mfma_f32_16x16x32_bf16 v[100:103], v[166:169], v[190:193], v[100:103]
	v_mfma_f32_16x16x32_bf16 v[100:103], v[162:165], v[186:189], v[100:103]
	v_mfma_f32_16x16x32_bf16 v[84:87], v[162:165], v[194:197], v[84:87]
	v_mfma_f32_16x16x32_bf16 v[84:87], v[166:169], v[198:201], v[84:87]
	v_mfma_f32_16x16x32_bf16 v[76:79], v[174:177], v[198:201], v[76:79]
	v_mfma_f32_16x16x32_bf16 v[76:79], v[170:173], v[194:197], v[76:79]
	v_mfma_f32_16x16x32_bf16 v[68:71], v[170:173], v[202:205], v[68:71]
	v_mfma_f32_16x16x32_bf16 v[68:71], v[174:177], v[210:213], v[68:71]
	v_mfma_f32_16x16x32_bf16 v[72:75], v[166:169], v[210:213], v[72:75]
	v_mfma_f32_16x16x32_bf16 v[72:75], v[162:165], v[202:205], v[72:75]
	s_barrier
	s_add_i32 s57, s57, s21
	s_mov_b32 m0, s57
	ds_read_b128 v[178:181], v149 offset:16384
	ds_read_b128 v[182:185], v149 offset:17408
	ds_read_b128 v[186:189], v149 offset:18432
	ds_read_b128 v[190:193], v149 offset:19456
	ds_read_b128 v[194:197], v149 offset:20480
	ds_read_b128 v[198:201], v149 offset:21504
	ds_read_b128 v[202:205], v149 offset:22528
	ds_read_b128 v[210:213], v149 offset:23552
	global_load_lds_dwordx4 v2, s[44:45]
	s_add_i32 m0, s57, 0x2000
	s_add_u32 s58, s44, 0x80000
	s_addc_u32 s59, s45, 0
	s_add_i32 s57, s60, s21
	global_load_lds_dwordx4 v132, s[44:45]
	s_mov_b32 m0, s57
	s_nop 0
	global_load_lds_dwordx4 v2, s[58:59]
	s_add_i32 m0, s57, 0x2000
	s_nop 0
	global_load_lds_dwordx4 v132, s[58:59]
	s_mov_b32 m0, s7
	s_nop 0
	global_load_lds_dwordx4 v136, s[46:47]
	s_mov_b32 m0, s11
	s_nop 0
	global_load_lds_dwordx4 v134, s[46:47]
	s_waitcnt vmcnt(8)
	s_waitcnt lgkmcnt(0)
	s_barrier
	s_waitcnt lgkmcnt(0)
	v_mfma_f32_16x16x32_bf16 v[64:67], v[142:145], v[178:181], v[64:67]
	v_mfma_f32_16x16x32_bf16 v[64:67], v[150:153], v[182:185], v[64:67]
	v_mfma_f32_16x16x32_bf16 v[60:63], v[158:161], v[182:185], v[60:63]
	v_mfma_f32_16x16x32_bf16 v[60:63], v[154:157], v[178:181], v[60:63]
	v_mfma_f32_16x16x32_bf16 v[48:51], v[154:157], v[186:189], v[48:51]
	v_mfma_f32_16x16x32_bf16 v[48:51], v[158:161], v[190:193], v[48:51]
	v_mfma_f32_16x16x32_bf16 v[56:59], v[150:153], v[190:193], v[56:59]
	v_mfma_f32_16x16x32_bf16 v[56:59], v[142:145], v[186:189], v[56:59]
	v_mfma_f32_16x16x32_bf16 v[40:43], v[142:145], v[194:197], v[40:43]
	v_mfma_f32_16x16x32_bf16 v[40:43], v[150:153], v[198:201], v[40:43]
	v_mfma_f32_16x16x32_bf16 v[32:35], v[158:161], v[198:201], v[32:35]
	v_mfma_f32_16x16x32_bf16 v[32:35], v[154:157], v[194:197], v[32:35]
	v_mfma_f32_16x16x32_bf16 v[16:19], v[154:157], v[202:205], v[16:19]
	v_mfma_f32_16x16x32_bf16 v[16:19], v[158:161], v[210:213], v[16:19]
	v_mfma_f32_16x16x32_bf16 v[24:27], v[150:153], v[210:213], v[24:27]
	v_mfma_f32_16x16x32_bf16 v[24:27], v[142:145], v[202:205], v[24:27]
	v_mfma_f32_16x16x32_bf16 v[52:55], v[162:165], v[178:181], v[52:55]
	v_mfma_f32_16x16x32_bf16 v[52:55], v[166:169], v[182:185], v[52:55]
	v_mfma_f32_16x16x32_bf16 v[44:47], v[174:177], v[182:185], v[44:47]
	v_mfma_f32_16x16x32_bf16 v[44:47], v[170:173], v[178:181], v[44:47]
	v_mfma_f32_16x16x32_bf16 v[28:31], v[170:173], v[186:189], v[28:31]
	v_mfma_f32_16x16x32_bf16 v[28:31], v[174:177], v[190:193], v[28:31]
	v_mfma_f32_16x16x32_bf16 v[36:39], v[166:169], v[190:193], v[36:39]
	v_mfma_f32_16x16x32_bf16 v[36:39], v[162:165], v[186:189], v[36:39]
	v_mfma_f32_16x16x32_bf16 v[20:23], v[162:165], v[194:197], v[20:23]
	v_mfma_f32_16x16x32_bf16 v[20:23], v[166:169], v[198:201], v[20:23]
	v_mfma_f32_16x16x32_bf16 v[12:15], v[174:177], v[198:201], v[12:15]
	v_mfma_f32_16x16x32_bf16 v[12:15], v[170:173], v[194:197], v[12:15]
	v_mfma_f32_16x16x32_bf16 v[4:7], v[170:173], v[202:205], v[4:7]
	v_mfma_f32_16x16x32_bf16 v[4:7], v[174:177], v[210:213], v[4:7]
	v_mfma_f32_16x16x32_bf16 v[8:11], v[166:169], v[210:213], v[8:11]
	v_mfma_f32_16x16x32_bf16 v[8:11], v[162:165], v[202:205], v[8:11]
	s_barrier
; #define PG8_STAGE(bufoff, gbase, voff) do { _Pragma("unroll") for (int _i = 0; _i < 2; ++_i) \
;         __builtin_amdgcn_global_load_lds((const unsigned*)((const char*)(gbase) + (voff)[_i]), (PG8_LAS unsigned*)(lds + (bufoff) + ldsw + _i * 8192), 16, 0, 0); } while (0)
; #define PG8_LDA(dst, b, h) do { _Pragma("unroll") for (int m = 0; m < 4; ++m) _Pragma("unroll") for (int k = 0; k < 2; ++k) dst[m][k] = *(const PG8_LAS bf16x8*)(lds + PG8_SA(b, h) + aoff + m * 2048 + k * 1024); } while (0)
; #define PG8_LDB(dst, b, h) do { _Pragma("unroll") for (int n = 0; n < 2; ++n) _Pragma("unroll") for (int k = 0; k < 2; ++k) dst[n][k] = *(const PG8_LAS bf16x8*)(lds + PG8_SB(b, h) + boff + n * 2048 + k * 1024); } while (0)
; #define PG8_MMA(ai, bj, At, Bt) do { __builtin_amdgcn_s_setprio(1); _Pragma("unroll") for (int m = 0; m < 4; ++m) _Pragma("unroll") for (int n = 0; n < 2; ++n) _Pragma("unroll") for (int k = 0; k < 2; ++k) \
;         acc[ai][bj][m][n] = __builtin_amdgcn_mfma_f32_16x16x32_bf16(Bt[n][k], At[m][k], acc[ai][bj][m][n], 0, 0, 0); __builtin_amdgcn_s_setprio(0); } while (0)
; #define PG8_WAIT_V(n) asm volatile("s_waitcnt vmcnt(" #n ")" ::: "memory")
; #define PG8_WAIT_L(n) asm volatile("s_waitcnt lgkmcnt(" #n ")" ::: "memory")
; #define PG8_BAR __builtin_amdgcn_s_barrier()
; #define PG8_SCHED __builtin_amdgcn_sched_barrier(0)
; template <class Epi, class Sched, bool ALIGN_EPI = true>
; __device__ __forceinline__ void gemm_phase(PG8_LAS unsigned char* lds, const Gemm g, const Sched& S, const Epi& E, const int tid) {
;     ...
;             PG8_LDB(B0, 1, 0); PG8_LDB(B1, 1, 1); PG8_SCHED; PG8_LDA(At, 1, 0); PG8_STAGE(PG8_SA(0, 1), a2 + hstepA, voffA);
;             PG8_WAIT_V(8); PG8_WAIT_L(0); PG8_BAR; PG8_MMA(0, 0, At, B0); PG8_MMA(0, 1, At, B1); PG8_BAR; PG8_SCHED;
;             PG8_LDA(At, 1, 1); PG8_STAGE(PG8_SB(1, 0), b3, voffB); PG8_STAGE(PG8_SB(1, 1), b3 + hstepB, voffB); PG8_STAGE(PG8_SA(1, 0), a3, voffA);
;             PG8_WAIT_V(8); PG8_WAIT_L(0); PG8_BAR; PG8_MMA(1, 0, At, B0); PG8_MMA(1, 1, At, B1); PG8_BAR; PG8_SCHED;
	s_add_i32 s57, 0, 0x18000
	s_add_i32 s58, 0, 0x1c000
	v_add_u32_e32 v158, s57, v147
	v_add_u32_e32 v174, s58, v147
	ds_read_b128 v[142:145], v158
	ds_read_b128 v[150:153], v158 offset:1024
	ds_read_b128 v[154:157], v158 offset:2048
	ds_read_b128 v[158:161], v158 offset:3072
	ds_read_b128 v[162:165], v174
	ds_read_b128 v[166:169], v174 offset:1024
	ds_read_b128 v[170:173], v174 offset:2048
	ds_read_b128 v[174:177], v174 offset:3072
	s_add_u32 s46, s46, 0x80000
	s_addc_u32 s47, s47, 0
	s_mov_b32 m0, s30
	ds_read_b128 v[178:181], v149 offset:32768
	ds_read_b128 v[182:185], v149 offset:33792
	ds_read_b128 v[186:189], v149 offset:34816
	ds_read_b128 v[190:193], v149 offset:35840
	ds_read_b128 v[194:197], v149 offset:36864
	ds_read_b128 v[198:201], v149 offset:37888
	ds_read_b128 v[202:205], v149 offset:38912
	ds_read_b128 v[210:213], v149 offset:39936
	global_load_lds_dwordx4 v136, s[46:47]
	s_mov_b32 m0, s48
	s_nop 0
	global_load_lds_dwordx4 v134, s[46:47]
	s_waitcnt vmcnt(8)
	s_waitcnt lgkmcnt(0)
	s_barrier
	s_waitcnt lgkmcnt(0)
	v_mfma_f32_16x16x32_bf16 v[128:131], v[142:145], v[178:181], v[128:131]
	v_mfma_f32_16x16x32_bf16 v[128:131], v[150:153], v[182:185], v[128:131]
	v_mfma_f32_16x16x32_bf16 v[124:127], v[158:161], v[182:185], v[124:127]
	v_mfma_f32_16x16x32_bf16 v[124:127], v[154:157], v[178:181], v[124:127]
	v_mfma_f32_16x16x32_bf16 v[112:115], v[154:157], v[186:189], v[112:115]
	v_mfma_f32_16x16x32_bf16 v[112:115], v[158:161], v[190:193], v[112:115]
	v_mfma_f32_16x16x32_bf16 v[120:123], v[150:153], v[190:193], v[120:123]
	v_mfma_f32_16x16x32_bf16 v[120:123], v[142:145], v[186:189], v[120:123]
	v_mfma_f32_16x16x32_bf16 v[104:107], v[142:145], v[194:197], v[104:107]
	v_mfma_f32_16x16x32_bf16 v[104:107], v[150:153], v[198:201], v[104:107]
	v_mfma_f32_16x16x32_bf16 v[96:99], v[158:161], v[198:201], v[96:99]
	v_mfma_f32_16x16x32_bf16 v[96:99], v[154:157], v[194:197], v[96:99]
	v_mfma_f32_16x16x32_bf16 v[80:83], v[154:157], v[202:205], v[80:83]
	v_mfma_f32_16x16x32_bf16 v[80:83], v[158:161], v[210:213], v[80:83]
	v_mfma_f32_16x16x32_bf16 v[88:91], v[150:153], v[210:213], v[88:91]
	v_mfma_f32_16x16x32_bf16 v[88:91], v[142:145], v[202:205], v[88:91]
	v_mfma_f32_16x16x32_bf16 v[116:119], v[162:165], v[178:181], v[116:119]
	v_mfma_f32_16x16x32_bf16 v[116:119], v[166:169], v[182:185], v[116:119]
	v_mfma_f32_16x16x32_bf16 v[108:111], v[174:177], v[182:185], v[108:111]
	v_mfma_f32_16x16x32_bf16 v[108:111], v[170:173], v[178:181], v[108:111]
	v_mfma_f32_16x16x32_bf16 v[92:95], v[170:173], v[186:189], v[92:95]
	v_mfma_f32_16x16x32_bf16 v[92:95], v[174:177], v[190:193], v[92:95]
	v_mfma_f32_16x16x32_bf16 v[100:103], v[166:169], v[190:193], v[100:103]
	v_mfma_f32_16x16x32_bf16 v[100:103], v[162:165], v[186:189], v[100:103]
	v_mfma_f32_16x16x32_bf16 v[84:87], v[162:165], v[194:197], v[84:87]
	v_mfma_f32_16x16x32_bf16 v[84:87], v[166:169], v[198:201], v[84:87]
	v_mfma_f32_16x16x32_bf16 v[76:79], v[174:177], v[198:201], v[76:79]
	v_mfma_f32_16x16x32_bf16 v[76:79], v[170:173], v[194:197], v[76:79]
	v_mfma_f32_16x16x32_bf16 v[68:71], v[170:173], v[202:205], v[68:71]
	v_mfma_f32_16x16x32_bf16 v[68:71], v[174:177], v[210:213], v[68:71]
	v_mfma_f32_16x16x32_bf16 v[72:75], v[166:169], v[210:213], v[72:75]
	v_mfma_f32_16x16x32_bf16 v[72:75], v[162:165], v[202:205], v[72:75]
	s_barrier
	s_add_u32 s96, s46, 0xfff80080
	s_addc_u32 s97, s47, -1
	s_add_i32 s46, s57, s21
	s_mov_b32 m0, s46
	ds_read_b128 v[178:181], v149 offset:49152
	ds_read_b128 v[182:185], v149 offset:50176
	ds_read_b128 v[186:189], v149 offset:51200
	ds_read_b128 v[190:193], v149 offset:52224
	ds_read_b128 v[194:197], v149 offset:53248
	ds_read_b128 v[198:201], v149 offset:54272
	ds_read_b128 v[202:205], v149 offset:55296
	ds_read_b128 v[210:213], v149 offset:56320
	s_add_u32 s98, s44, 0x80
	s_addc_u32 s99, s45, 0
	global_load_lds_dwordx4 v2, s[98:99]
	s_add_i32 m0, s46, 0x2000
	s_add_u32 s44, s44, 0x80080
	s_addc_u32 s45, s45, 0
	s_add_i32 s46, s58, s21
	global_load_lds_dwordx4 v132, s[98:99]
	s_mov_b32 m0, s46
	s_nop 0
	global_load_lds_dwordx4 v2, s[44:45]
	s_add_i32 m0, s46, 0x2000
	s_nop 0
	global_load_lds_dwordx4 v132, s[44:45]
	s_mov_b32 m0, s49
	s_nop 0
	global_load_lds_dwordx4 v136, s[96:97]
	s_mov_b32 m0, s50
	s_nop 0
	global_load_lds_dwordx4 v134, s[96:97]
	s_waitcnt vmcnt(8)
	s_waitcnt lgkmcnt(0)
	s_barrier
	s_waitcnt lgkmcnt(0)
	v_mfma_f32_16x16x32_bf16 v[64:67], v[142:145], v[178:181], v[64:67]
	v_mfma_f32_16x16x32_bf16 v[64:67], v[150:153], v[182:185], v[64:67]
	v_mfma_f32_16x16x32_bf16 v[60:63], v[158:161], v[182:185], v[60:63]
	v_mfma_f32_16x16x32_bf16 v[60:63], v[154:157], v[178:181], v[60:63]
	v_mfma_f32_16x16x32_bf16 v[48:51], v[154:157], v[186:189], v[48:51]
	v_mfma_f32_16x16x32_bf16 v[48:51], v[158:161], v[190:193], v[48:51]
	v_mfma_f32_16x16x32_bf16 v[56:59], v[150:153], v[190:193], v[56:59]
	v_mfma_f32_16x16x32_bf16 v[56:59], v[142:145], v[186:189], v[56:59]
	v_mfma_f32_16x16x32_bf16 v[40:43], v[142:145], v[194:197], v[40:43]
	v_mfma_f32_16x16x32_bf16 v[40:43], v[150:153], v[198:201], v[40:43]
	v_mfma_f32_16x16x32_bf16 v[32:35], v[158:161], v[198:201], v[32:35]
	v_mfma_f32_16x16x32_bf16 v[32:35], v[154:157], v[194:197], v[32:35]
	v_mfma_f32_16x16x32_bf16 v[16:19], v[154:157], v[202:205], v[16:19]
	v_mfma_f32_16x16x32_bf16 v[16:19], v[158:161], v[210:213], v[16:19]
	v_mfma_f32_16x16x32_bf16 v[24:27], v[150:153], v[210:213], v[24:27]
	v_mfma_f32_16x16x32_bf16 v[24:27], v[142:145], v[202:205], v[24:27]
	v_mfma_f32_16x16x32_bf16 v[52:55], v[162:165], v[178:181], v[52:55]
	v_mfma_f32_16x16x32_bf16 v[52:55], v[166:169], v[182:185], v[52:55]
	v_mfma_f32_16x16x32_bf16 v[44:47], v[174:177], v[182:185], v[44:47]
	v_mfma_f32_16x16x32_bf16 v[44:47], v[170:173], v[178:181], v[44:47]
	v_mfma_f32_16x16x32_bf16 v[28:31], v[170:173], v[186:189], v[28:31]
	v_mfma_f32_16x16x32_bf16 v[28:31], v[174:177], v[190:193], v[28:31]
	v_mfma_f32_16x16x32_bf16 v[36:39], v[166:169], v[190:193], v[36:39]
	v_mfma_f32_16x16x32_bf16 v[36:39], v[162:165], v[186:189], v[36:39]
	v_mfma_f32_16x16x32_bf16 v[20:23], v[162:165], v[194:197], v[20:23]
	v_mfma_f32_16x16x32_bf16 v[20:23], v[166:169], v[198:201], v[20:23]
	v_mfma_f32_16x16x32_bf16 v[12:15], v[174:177], v[198:201], v[12:15]
	v_mfma_f32_16x16x32_bf16 v[12:15], v[170:173], v[194:197], v[12:15]
	v_mfma_f32_16x16x32_bf16 v[4:7], v[170:173], v[202:205], v[4:7]
	v_mfma_f32_16x16x32_bf16 v[4:7], v[174:177], v[210:213], v[4:7]
	v_mfma_f32_16x16x32_bf16 v[8:11], v[166:169], v[210:213], v[8:11]
	v_mfma_f32_16x16x32_bf16 v[8:11], v[162:165], v[202:205], v[8:11]
	s_barrier
; __device__ __forceinline__ unsigned cvt_pk_bf16(float lo, float hi) { unsigned r; asm volatile("v_cvt_pk_bf16_f32 %0, %1, %2" : "=v"(r) : "v"(lo), "v"(hi)); return r; }
; #define PG8_WAIT_V(n) asm volatile("s_waitcnt vmcnt(" #n ")" ::: "memory")
; #define PG8_BAR __builtin_amdgcn_s_barrier()
;     __device__ __forceinline__ void operator()(const f32x4 (&acc)[2][2][4][2], const Unit& u, int wr, int wc, int fr, int fq) const {
;         const int row0 = u.pm * BM + wr * 64 + fr; const int col0 = u.pn * BM + wc * 32 + 8 * fq;
; #pragma unroll
;         for (int ai = 0; ai < 2; ++ai)
; #pragma unroll
;             for (int m = 0; m < 4; ++m) { bf16_t* rowp = O + (size_t)(row0 + ai * HALF + m * 16) * ldc + col0;
; #pragma unroll
;                 for (int bj = 0; bj < 2; ++bj) { const f32x4 v0 = acc[ai][bj][m][0], v1 = acc[ai][bj][m][1];
;                     u32x4 w; w.x = cvt_pk_bf16(v0[0], v0[1]); w.y = cvt_pk_bf16(v0[2], v0[3]); w.z = cvt_pk_bf16(v1[0], v1[1]); w.w = cvt_pk_bf16(v1[2], v1[3]);
;                     *(u32x4*)(rowp + bj * HALF) = w; } }
; template <class Epi, class Sched, bool ALIGN_EPI = true>
; __device__ __forceinline__ void gemm_phase(PG8_LAS unsigned char* lds, const Gemm g, const Sched& S, const Epi& E, const int tid) {
;     ...
;         }
;         if constexpr (ALIGN_EPI) { if (wr == 0) PG8_BAR; }
;         E(acc, cur, wr, wc, fr, fq); S.done(cur);
;         if (!has_next) break;
; #pragma unroll
;         for (int a = 0; a < 2; ++a)
; #pragma unroll
;             for (int b = 0; b < 2; ++b)
; #pragma unroll
;                 for (int m = 0; m < 4; ++m)
; #pragma unroll
;                     for (int n = 0; n < 2; ++n) acc[a][b][m][n] = (f32x4){0.f, 0.f, 0.f, 0.f};
;         cur = nxt; cA = nA; cB = nB; ++ui;
;         if constexpr (ALIGN_EPI) { if (wr == 1) PG8_BAR; }
;     }
;     PG8_WAIT_V(0);
;     if constexpr (!ALIGN_EPI) { if (wr == 0) PG8_BAR; }
;     PG8_BAR;
	s_add_i32 s56, s56, 2
	s_add_u32 s42, s42, 0x100
	s_addc_u32 s43, s43, 0
	s_add_u32 s54, s54, 0x100
	s_addc_u32 s55, s55, 0
	s_cmp_gt_u32 s56, 29
	s_cbranch_scc0 .LBB0_514
	v_lshl_or_b32 v144, s10, 8, v148
	v_lshl_add_u32 v152, s6, 8, v146
	v_ashrrev_i32_e32 v145, 31, v144
	v_mov_b64_e32 v[142:143], s[0:1]
	s_movk_i32 s3, 0x3200
	v_mad_i64_i32 v[150:151], s[42:43], v152, s3, v[142:143]
	v_lshlrev_b64 v[144:145], 1, v[144:145]
	v_lshl_add_u64 v[150:151], v[150:151], 0, v[144:145]
	v_cvt_pk_bf16_f32 v128, v128, v129
	v_cvt_pk_bf16_f32 v129, v130, v131
	v_cvt_pk_bf16_f32 v130, v124, v125
	v_cvt_pk_bf16_f32 v131, v126, v127
	global_store_dwordx4 v[150:151], v[128:131], off nt
	v_cvt_pk_bf16_f32 v116, v116, v117
	v_cvt_pk_bf16_f32 v117, v118, v119
	v_cvt_pk_bf16_f32 v118, v108, v109
	v_or_b32_e32 v108, 16, v152
	v_mad_i64_i32 v[108:109], s[42:43], v108, s3, v[142:143]
	v_cvt_pk_bf16_f32 v119, v110, v111
	global_store_dwordx4 v[150:151], v[116:119], off offset:256 nt
	s_and_b64 vcc, exec, s[4:5]
	s_mov_b32 s10, s22
	v_lshl_add_u64 v[116:117], v[108:109], 0, v[144:145]
	v_cvt_pk_bf16_f32 v108, v120, v121
	v_cvt_pk_bf16_f32 v109, v122, v123
	v_cvt_pk_bf16_f32 v110, v112, v113
	v_cvt_pk_bf16_f32 v111, v114, v115
	global_store_dwordx4 v[116:117], v[108:111], off nt
	v_cvt_pk_bf16_f32 v100, v100, v101
	v_cvt_pk_bf16_f32 v101, v102, v103
	v_cvt_pk_bf16_f32 v102, v92, v93
	v_or_b32_e32 v92, 32, v152
	v_mad_i64_i32 v[92:93], s[42:43], v92, s3, v[142:143]
	v_cvt_pk_bf16_f32 v103, v94, v95
	global_store_dwordx4 v[116:117], v[100:103], off offset:256 nt
	s_mov_b32 s6, s12
	s_mov_b64 s[44:45], s[40:41]
	v_lshl_add_u64 v[100:101], v[92:93], 0, v[144:145]
	v_cvt_pk_bf16_f32 v92, v104, v105
	v_cvt_pk_bf16_f32 v93, v106, v107
	v_cvt_pk_bf16_f32 v94, v96, v97
	v_cvt_pk_bf16_f32 v95, v98, v99
	global_store_dwordx4 v[100:101], v[92:95], off nt
	v_cvt_pk_bf16_f32 v84, v84, v85
	v_cvt_pk_bf16_f32 v85, v86, v87
	v_cvt_pk_bf16_f32 v86, v76, v77
	v_or_b32_e32 v76, 48, v152
	v_mad_i64_i32 v[76:77], s[42:43], v76, s3, v[142:143]
	v_cvt_pk_bf16_f32 v87, v78, v79
	global_store_dwordx4 v[100:101], v[84:87], off offset:256 nt
	s_nop 1
	v_lshl_add_u64 v[84:85], v[76:77], 0, v[144:145]
	v_cvt_pk_bf16_f32 v76, v88, v89
	v_cvt_pk_bf16_f32 v77, v90, v91
	v_cvt_pk_bf16_f32 v78, v80, v81
	v_cvt_pk_bf16_f32 v79, v82, v83
	global_store_dwordx4 v[84:85], v[76:79], off nt
	v_cvt_pk_bf16_f32 v72, v72, v73
	v_cvt_pk_bf16_f32 v73, v74, v75
	v_cvt_pk_bf16_f32 v74, v68, v69
	v_add_u32_e32 v68, 0x80, v152
	v_mad_i64_i32 v[68:69], s[42:43], v68, s3, v[142:143]
	v_lshl_add_u64 v[68:69], v[68:69], 0, v[144:145]
	v_cvt_pk_bf16_f32 v75, v70, v71
	global_store_dwordx4 v[84:85], v[72:75], off offset:256 nt
	v_cvt_pk_bf16_f32 v64, v64, v65
	v_cvt_pk_bf16_f32 v65, v66, v67
	v_cvt_pk_bf16_f32 v66, v60, v61
	v_cvt_pk_bf16_f32 v67, v62, v63
	global_store_dwordx4 v[68:69], v[64:67], off nt
	v_cvt_pk_bf16_f32 v52, v52, v53
	v_cvt_pk_bf16_f32 v53, v54, v55
	v_cvt_pk_bf16_f32 v54, v44, v45
	v_add_u32_e32 v44, 0x90, v152
	v_mad_i64_i32 v[44:45], s[42:43], v44, s3, v[142:143]
	v_cvt_pk_bf16_f32 v55, v46, v47
	global_store_dwordx4 v[68:69], v[52:55], off offset:256 nt
	s_nop 1
	v_lshl_add_u64 v[52:53], v[44:45], 0, v[144:145]
	v_cvt_pk_bf16_f32 v44, v56, v57
	v_cvt_pk_bf16_f32 v45, v58, v59
	v_cvt_pk_bf16_f32 v46, v48, v49
	v_cvt_pk_bf16_f32 v47, v50, v51
	global_store_dwordx4 v[52:53], v[44:47], off nt
	v_cvt_pk_bf16_f32 v36, v36, v37
	v_cvt_pk_bf16_f32 v37, v38, v39
	v_cvt_pk_bf16_f32 v38, v28, v29
	v_add_u32_e32 v28, 0xa0, v152
	v_mad_i64_i32 v[28:29], s[42:43], v28, s3, v[142:143]
	v_cvt_pk_bf16_f32 v39, v30, v31
	global_store_dwordx4 v[52:53], v[36:39], off offset:256 nt
	s_nop 1
	v_lshl_add_u64 v[36:37], v[28:29], 0, v[144:145]
	v_cvt_pk_bf16_f32 v28, v40, v41
	v_cvt_pk_bf16_f32 v29, v42, v43
	v_cvt_pk_bf16_f32 v30, v32, v33
	v_cvt_pk_bf16_f32 v31, v34, v35
	global_store_dwordx4 v[36:37], v[28:31], off nt
	v_cvt_pk_bf16_f32 v20, v20, v21
	v_cvt_pk_bf16_f32 v21, v22, v23
	v_cvt_pk_bf16_f32 v22, v12, v13
	v_add_u32_e32 v12, 0xb0, v152
	v_mad_i64_i32 v[12:13], s[42:43], v12, s3, v[142:143]
	v_cvt_pk_bf16_f32 v23, v14, v15
	global_store_dwordx4 v[36:37], v[20:23], off offset:256 nt
	s_mov_b64 s[42:43], s[38:39]
	s_nop 0
	v_lshl_add_u64 v[20:21], v[12:13], 0, v[144:145]
	v_cvt_pk_bf16_f32 v12, v24, v25
	v_cvt_pk_bf16_f32 v13, v26, v27
	v_cvt_pk_bf16_f32 v14, v16, v17
	v_cvt_pk_bf16_f32 v15, v18, v19
	global_store_dwordx4 v[20:21], v[12:15], off nt
	v_cvt_pk_bf16_f32 v8, v8, v9
	v_cvt_pk_bf16_f32 v9, v10, v11
	v_cvt_pk_bf16_f32 v10, v4, v5
	v_cvt_pk_bf16_f32 v11, v6, v7
	global_store_dwordx4 v[20:21], v[8:11], off offset:256 nt
	s_cbranch_vccz .LBB0_507
	s_waitcnt vmcnt(0)
	s_cmpk_gt_u32 s8, 0xff
	s_cbranch_scc1 .LBB0_518
	s_barrier
